# context-query attention item hand-written (operand loads in flight, no per-load waits)
# speedup vs baseline: 1.5952x; 1.0007x over previous
.LBB0_610:
	s_and_b32 s0, s12, 7
	s_bfe_u32 s1, s12, 0x10005
	s_lshl_b32 s1, s1, 3
	s_or_b32 s0, s0, s1
	s_bfe_u32 s6, s12, 0x20003
	s_lshr_b32 s8, s12, 6
	v_and_b32_e32 v206, 15, v205
	v_lshrrev_b32_e32 v207, 4, v205
	s_lshl_b32 s7, s8, 8
	s_lshl_b32 s1, s0, 4
	s_add_i32 s7, s7, s1
	s_lshl_b32 s16, s6, 7
	s_add_u32 s16, s16, 0x5e00000
	s_add_u32 s18, s4, s16
	s_addc_u32 s19, s5, 0
	s_mul_i32 s10, s7, 0xe00
	s_add_u32 s20, s18, s10
	s_addc_u32 s21, s19, 0
	v_mul_u32_u24_e32 v208, 0xe00, v206
	v_lshl_add_u32 v208, v207, 4, v208
	global_load_dwordx4 v[128:131], v208, s[20:21] offset:1536
	global_load_dwordx4 v[132:135], v208, s[20:21] offset:1600
	v_lshrrev_b32_e32 v209, 2, v206
	v_and_b32_e32 v210, 3, v206
	v_lshl_add_u32 v209, v209, 3, v210
	v_mul_u32_u24_e32 v209, 0xe00, v209
	v_lshl_add_u32 v209, v207, 4, v209
	s_lshl_b32 s10, s8, 8
	s_mul_i32 s10, s10, 0xe00
	s_add_u32 s24, s18, s10
	s_addc_u32 s25, s19, 0
	global_load_dwordx4 v[64:67], v209, s[24:25] offset:2048
	global_load_dwordx4 v[68:71], v209, s[24:25] offset:2112
	s_add_u32 s24, s24, 0x3800
	s_addc_u32 s25, s25, 0
	global_load_dwordx4 v[72:75], v209, s[24:25] offset:2048
	global_load_dwordx4 v[76:79], v209, s[24:25] offset:2112
	s_add_u32 s24, s24, 0x18800
	s_addc_u32 s25, s25, 0
	global_load_dwordx4 v[80:83], v209, s[24:25] offset:2048
	global_load_dwordx4 v[84:87], v209, s[24:25] offset:2112
	s_add_u32 s24, s24, 0x3800
	s_addc_u32 s25, s25, 0
	global_load_dwordx4 v[88:91], v209, s[24:25] offset:2048
	global_load_dwordx4 v[92:95], v209, s[24:25] offset:2112
	s_add_u32 s24, s24, 0x18800
	s_addc_u32 s25, s25, 0
	global_load_dwordx4 v[96:99], v209, s[24:25] offset:2048
	global_load_dwordx4 v[100:103], v209, s[24:25] offset:2112
	s_add_u32 s24, s24, 0x3800
	s_addc_u32 s25, s25, 0
	global_load_dwordx4 v[104:107], v209, s[24:25] offset:2048
	global_load_dwordx4 v[108:111], v209, s[24:25] offset:2112
	s_add_u32 s24, s24, 0x18800
	s_addc_u32 s25, s25, 0
	global_load_dwordx4 v[112:115], v209, s[24:25] offset:2048
	global_load_dwordx4 v[116:119], v209, s[24:25] offset:2112
	s_add_u32 s24, s24, 0x3800
	s_addc_u32 s25, s25, 0
	global_load_dwordx4 v[120:123], v209, s[24:25] offset:2048
	global_load_dwordx4 v[124:127], v209, s[24:25] offset:2112
	s_add_u32 s24, s24, 0x18800
	s_addc_u32 s25, s25, 0
	v_lshlrev_b32_e32 v210, 9, v206
	v_lshl_add_u32 v210, v207, 4, v210
	s_lshl_b32 s10, s8, 8
	s_lshl_b32 s11, s6, 6
	s_add_i32 s10, s10, s11
	s_lshl_b32 s10, s10, 9
	s_add_u32 s10, s10, 0xa200000
	s_add_u32 s16, s4, s10
	s_addc_u32 s17, s5, 0
	s_add_u32 s22, s16, 0x2000
	s_addc_u32 s23, s17, 0
	s_add_u32 s26, s22, 0x2000
	s_addc_u32 s27, s23, 0
	s_add_u32 s36, s26, 0x2000
	s_addc_u32 s37, s27, 0
	s_mul_i32 s10, s7, 0x600
	s_lshl_b32 s11, s6, 7
	s_add_i32 s10, s10, s11
	s_add_u32 s38, s10, 0xdf00400
	s_waitcnt vmcnt(15)
	v_mfma_f32_16x16x32_bf16 v[0:3], v[64:67], v[128:131], 0
	s_waitcnt vmcnt(14)
	v_mfma_f32_16x16x32_bf16 v[0:3], v[68:71], v[132:135], v[0:3]
	global_load_dwordx4 v[64:67], v209, s[24:25] offset:2048
	global_load_dwordx4 v[68:71], v209, s[24:25] offset:2112
	s_add_u32 s24, s24, 0x3800
	s_addc_u32 s25, s25, 0
	s_waitcnt vmcnt(15)
	v_mfma_f32_16x16x32_bf16 v[4:7], v[72:75], v[128:131], 0
	s_waitcnt vmcnt(14)
	v_mfma_f32_16x16x32_bf16 v[4:7], v[76:79], v[132:135], v[4:7]
	global_load_dwordx4 v[72:75], v209, s[24:25] offset:2048
	global_load_dwordx4 v[76:79], v209, s[24:25] offset:2112
	s_add_u32 s24, s24, 0x18800
	s_addc_u32 s25, s25, 0
	s_waitcnt vmcnt(15)
	v_mfma_f32_16x16x32_bf16 v[8:11], v[80:83], v[128:131], 0
	s_waitcnt vmcnt(14)
	v_mfma_f32_16x16x32_bf16 v[8:11], v[84:87], v[132:135], v[8:11]
	global_load_dwordx4 v[80:83], v209, s[24:25] offset:2048
	global_load_dwordx4 v[84:87], v209, s[24:25] offset:2112
	s_add_u32 s24, s24, 0x3800
	s_addc_u32 s25, s25, 0
	s_waitcnt vmcnt(15)
	v_mfma_f32_16x16x32_bf16 v[12:15], v[88:91], v[128:131], 0
	s_waitcnt vmcnt(14)
	v_mfma_f32_16x16x32_bf16 v[12:15], v[92:95], v[132:135], v[12:15]
	global_load_dwordx4 v[88:91], v209, s[24:25] offset:2048
	global_load_dwordx4 v[92:95], v209, s[24:25] offset:2112
	s_add_u32 s24, s24, 0x18800
	s_addc_u32 s25, s25, 0
	s_waitcnt vmcnt(15)
	v_mfma_f32_16x16x32_bf16 v[16:19], v[96:99], v[128:131], 0
	s_waitcnt vmcnt(14)
	v_mfma_f32_16x16x32_bf16 v[16:19], v[100:103], v[132:135], v[16:19]
	global_load_dwordx4 v[96:99], v209, s[24:25] offset:2048
	global_load_dwordx4 v[100:103], v209, s[24:25] offset:2112
	s_add_u32 s24, s24, 0x3800
	s_addc_u32 s25, s25, 0
	s_waitcnt vmcnt(15)
	v_mfma_f32_16x16x32_bf16 v[20:23], v[104:107], v[128:131], 0
	s_waitcnt vmcnt(14)
	v_mfma_f32_16x16x32_bf16 v[20:23], v[108:111], v[132:135], v[20:23]
	global_load_dwordx4 v[104:107], v209, s[24:25] offset:2048
	global_load_dwordx4 v[108:111], v209, s[24:25] offset:2112
	s_add_u32 s24, s24, 0x18800
	s_addc_u32 s25, s25, 0
	s_waitcnt vmcnt(15)
	v_mfma_f32_16x16x32_bf16 v[24:27], v[112:115], v[128:131], 0
	s_waitcnt vmcnt(14)
	v_mfma_f32_16x16x32_bf16 v[24:27], v[116:119], v[132:135], v[24:27]
	global_load_dwordx4 v[112:115], v209, s[24:25] offset:2048
	global_load_dwordx4 v[116:119], v209, s[24:25] offset:2112
	s_add_u32 s24, s24, 0x3800
	s_addc_u32 s25, s25, 0
	s_waitcnt vmcnt(15)
	v_mfma_f32_16x16x32_bf16 v[28:31], v[120:123], v[128:131], 0
	s_waitcnt vmcnt(14)
	v_mfma_f32_16x16x32_bf16 v[28:31], v[124:127], v[132:135], v[28:31]
	global_load_dwordx4 v[120:123], v209, s[24:25] offset:2048
	global_load_dwordx4 v[124:127], v209, s[24:25] offset:2112
	s_waitcnt vmcnt(15)
	v_mfma_f32_16x16x32_bf16 v[32:35], v[64:67], v[128:131], 0
	s_waitcnt vmcnt(14)
	v_mfma_f32_16x16x32_bf16 v[32:35], v[68:71], v[132:135], v[32:35]
	s_waitcnt vmcnt(13)
	v_mfma_f32_16x16x32_bf16 v[36:39], v[72:75], v[128:131], 0
	s_waitcnt vmcnt(12)
	v_mfma_f32_16x16x32_bf16 v[36:39], v[76:79], v[132:135], v[36:39]
	s_waitcnt vmcnt(11)
	v_mfma_f32_16x16x32_bf16 v[40:43], v[80:83], v[128:131], 0
	s_waitcnt vmcnt(10)
	v_mfma_f32_16x16x32_bf16 v[40:43], v[84:87], v[132:135], v[40:43]
	s_waitcnt vmcnt(9)
	v_mfma_f32_16x16x32_bf16 v[44:47], v[88:91], v[128:131], 0
	s_waitcnt vmcnt(8)
	v_mfma_f32_16x16x32_bf16 v[44:47], v[92:95], v[132:135], v[44:47]
	s_waitcnt vmcnt(7)
	v_mfma_f32_16x16x32_bf16 v[48:51], v[96:99], v[128:131], 0
	s_waitcnt vmcnt(6)
	v_mfma_f32_16x16x32_bf16 v[48:51], v[100:103], v[132:135], v[48:51]
	s_waitcnt vmcnt(5)
	v_mfma_f32_16x16x32_bf16 v[52:55], v[104:107], v[128:131], 0
	s_waitcnt vmcnt(4)
	v_mfma_f32_16x16x32_bf16 v[52:55], v[108:111], v[132:135], v[52:55]
	s_waitcnt vmcnt(3)
	v_mfma_f32_16x16x32_bf16 v[56:59], v[112:115], v[128:131], 0
	s_waitcnt vmcnt(2)
	v_mfma_f32_16x16x32_bf16 v[56:59], v[116:119], v[132:135], v[56:59]
	s_waitcnt vmcnt(1)
	v_mfma_f32_16x16x32_bf16 v[60:63], v[120:123], v[128:131], 0
	s_waitcnt vmcnt(0)
	v_mfma_f32_16x16x32_bf16 v[60:63], v[124:127], v[132:135], v[60:63]
	global_load_dwordx4 v[64:67], v210, s[16:17] offset:0
	global_load_dwordx4 v[68:71], v210, s[22:23] offset:0
	global_load_dwordx4 v[72:75], v210, s[26:27] offset:0
	global_load_dwordx4 v[76:79], v210, s[36:37] offset:0
	global_load_dwordx4 v[80:83], v210, s[16:17] offset:64
	global_load_dwordx4 v[84:87], v210, s[22:23] offset:64
	global_load_dwordx4 v[88:91], v210, s[26:27] offset:64
	global_load_dwordx4 v[92:95], v210, s[36:37] offset:64
	global_load_dwordx4 v[96:99], v210, s[16:17] offset:128
	global_load_dwordx4 v[100:103], v210, s[22:23] offset:128
	global_load_dwordx4 v[104:107], v210, s[26:27] offset:128
	global_load_dwordx4 v[108:111], v210, s[36:37] offset:128
	global_load_dwordx4 v[112:115], v210, s[16:17] offset:192
	global_load_dwordx4 v[116:119], v210, s[22:23] offset:192
	global_load_dwordx4 v[120:123], v210, s[26:27] offset:192
	global_load_dwordx4 v[124:127], v210, s[36:37] offset:192
	s_nop 7
	v_max3_f32 v214, v0, v1, v2
	v_max3_f32 v214, v214, v3, v4
	v_max3_f32 v214, v214, v5, v6
	v_max3_f32 v214, v214, v7, v8
	v_max3_f32 v214, v214, v9, v10
	v_max3_f32 v214, v214, v11, v12
	v_max3_f32 v214, v214, v13, v14
	v_max3_f32 v214, v214, v15, v16
	v_max3_f32 v214, v214, v17, v18
	v_max3_f32 v214, v214, v19, v20
	v_max3_f32 v214, v214, v21, v22
	v_max3_f32 v214, v214, v23, v24
	v_max3_f32 v214, v214, v25, v26
	v_max3_f32 v214, v214, v27, v28
	v_max3_f32 v214, v214, v29, v30
	v_max3_f32 v214, v214, v31, v32
	v_max3_f32 v214, v214, v33, v34
	v_max3_f32 v214, v214, v35, v36
	v_max3_f32 v214, v214, v37, v38
	v_max3_f32 v214, v214, v39, v40
	v_max3_f32 v214, v214, v41, v42
	v_max3_f32 v214, v214, v43, v44
	v_max3_f32 v214, v214, v45, v46
	v_max3_f32 v214, v214, v47, v48
	v_max3_f32 v214, v214, v49, v50
	v_max3_f32 v214, v214, v51, v52
	v_max3_f32 v214, v214, v53, v54
	v_max3_f32 v214, v214, v55, v56
	v_max3_f32 v214, v214, v57, v58
	v_max3_f32 v214, v214, v59, v60
	v_max3_f32 v214, v214, v61, v62
	v_max_f32_e32 v214, v214, v63
	v_xor_b32_e32 v215, 16, v205
	v_lshlrev_b32_e32 v215, 2, v215
	v_xor_b32_e32 v216, 32, v205
	v_lshlrev_b32_e32 v216, 2, v216
	ds_bpermute_b32 v136, v215, v214
	s_waitcnt lgkmcnt(0)
	v_max_f32_e32 v214, v214, v136
	ds_bpermute_b32 v136, v216, v214
	s_waitcnt lgkmcnt(0)
	v_max_f32_e32 v214, v214, v136
	v_mul_f32_e32 v214, 0xbe38aa3b, v214
	s_mov_b32 s10, 0x3e38aa3b
	v_mov_b32_e32 v212, 0
	v_mov_b32_e32 v213, 0
	v_fma_f32 v0, v0, s10, v214
	v_fma_f32 v1, v1, s10, v214
	v_fma_f32 v2, v2, s10, v214
	v_fma_f32 v3, v3, s10, v214
	v_fma_f32 v4, v4, s10, v214
	v_fma_f32 v5, v5, s10, v214
	v_fma_f32 v6, v6, s10, v214
	v_fma_f32 v7, v7, s10, v214
	v_exp_f32_e32 v0, v0
	v_exp_f32_e32 v1, v1
	v_exp_f32_e32 v2, v2
	v_exp_f32_e32 v3, v3
	v_exp_f32_e32 v4, v4
	v_exp_f32_e32 v5, v5
	v_exp_f32_e32 v6, v6
	v_exp_f32_e32 v7, v7
	s_nop 0
	v_add_f32_e32 v212, v212, v0
	v_add_f32_e32 v213, v213, v1
	v_add_f32_e32 v212, v212, v2
	v_add_f32_e32 v213, v213, v3
	v_add_f32_e32 v212, v212, v4
	v_add_f32_e32 v213, v213, v5
	v_add_f32_e32 v212, v212, v6
	v_add_f32_e32 v213, v213, v7
	v_cvt_pk_bf16_f32 v0, v0, v1
	v_cvt_pk_bf16_f32 v1, v2, v3
	v_cvt_pk_bf16_f32 v2, v4, v5
	v_cvt_pk_bf16_f32 v3, v6, v7
	v_fma_f32 v8, v8, s10, v214
	v_fma_f32 v9, v9, s10, v214
	v_fma_f32 v10, v10, s10, v214
	v_fma_f32 v11, v11, s10, v214
	v_fma_f32 v12, v12, s10, v214
	v_fma_f32 v13, v13, s10, v214
	v_fma_f32 v14, v14, s10, v214
	v_fma_f32 v15, v15, s10, v214
	v_exp_f32_e32 v8, v8
	v_exp_f32_e32 v9, v9
	v_exp_f32_e32 v10, v10
	v_exp_f32_e32 v11, v11
	v_exp_f32_e32 v12, v12
	v_exp_f32_e32 v13, v13
	v_exp_f32_e32 v14, v14
	v_exp_f32_e32 v15, v15
	s_nop 0
	v_add_f32_e32 v212, v212, v8
	v_add_f32_e32 v213, v213, v9
	v_add_f32_e32 v212, v212, v10
	v_add_f32_e32 v213, v213, v11
	v_add_f32_e32 v212, v212, v12
	v_add_f32_e32 v213, v213, v13
	v_add_f32_e32 v212, v212, v14
	v_add_f32_e32 v213, v213, v15
	v_cvt_pk_bf16_f32 v8, v8, v9
	v_cvt_pk_bf16_f32 v9, v10, v11
	v_cvt_pk_bf16_f32 v10, v12, v13
	v_cvt_pk_bf16_f32 v11, v14, v15
	v_fma_f32 v16, v16, s10, v214
	v_fma_f32 v17, v17, s10, v214
	v_fma_f32 v18, v18, s10, v214
	v_fma_f32 v19, v19, s10, v214
	v_fma_f32 v20, v20, s10, v214
	v_fma_f32 v21, v21, s10, v214
	v_fma_f32 v22, v22, s10, v214
	v_fma_f32 v23, v23, s10, v214
	v_exp_f32_e32 v16, v16
	v_exp_f32_e32 v17, v17
	v_exp_f32_e32 v18, v18
	v_exp_f32_e32 v19, v19
	v_exp_f32_e32 v20, v20
	v_exp_f32_e32 v21, v21
	v_exp_f32_e32 v22, v22
	v_exp_f32_e32 v23, v23
	s_nop 0
	v_add_f32_e32 v212, v212, v16
	v_add_f32_e32 v213, v213, v17
	v_add_f32_e32 v212, v212, v18
	v_add_f32_e32 v213, v213, v19
	v_add_f32_e32 v212, v212, v20
	v_add_f32_e32 v213, v213, v21
	v_add_f32_e32 v212, v212, v22
	v_add_f32_e32 v213, v213, v23
	v_cvt_pk_bf16_f32 v16, v16, v17
	v_cvt_pk_bf16_f32 v17, v18, v19
	v_cvt_pk_bf16_f32 v18, v20, v21
	v_cvt_pk_bf16_f32 v19, v22, v23
	v_fma_f32 v24, v24, s10, v214
	v_fma_f32 v25, v25, s10, v214
	v_fma_f32 v26, v26, s10, v214
	v_fma_f32 v27, v27, s10, v214
	v_fma_f32 v28, v28, s10, v214
	v_fma_f32 v29, v29, s10, v214
	v_fma_f32 v30, v30, s10, v214
	v_fma_f32 v31, v31, s10, v214
	v_exp_f32_e32 v24, v24
	v_exp_f32_e32 v25, v25
	v_exp_f32_e32 v26, v26
	v_exp_f32_e32 v27, v27
	v_exp_f32_e32 v28, v28
	v_exp_f32_e32 v29, v29
	v_exp_f32_e32 v30, v30
	v_exp_f32_e32 v31, v31
	s_nop 0
	v_add_f32_e32 v212, v212, v24
	v_add_f32_e32 v213, v213, v25
	v_add_f32_e32 v212, v212, v26
	v_add_f32_e32 v213, v213, v27
	v_add_f32_e32 v212, v212, v28
	v_add_f32_e32 v213, v213, v29
	v_add_f32_e32 v212, v212, v30
	v_add_f32_e32 v213, v213, v31
	v_cvt_pk_bf16_f32 v24, v24, v25
	v_cvt_pk_bf16_f32 v25, v26, v27
	v_cvt_pk_bf16_f32 v26, v28, v29
	v_cvt_pk_bf16_f32 v27, v30, v31
	v_fma_f32 v32, v32, s10, v214
	v_fma_f32 v33, v33, s10, v214
	v_fma_f32 v34, v34, s10, v214
	v_fma_f32 v35, v35, s10, v214
	v_fma_f32 v36, v36, s10, v214
	v_fma_f32 v37, v37, s10, v214
	v_fma_f32 v38, v38, s10, v214
	v_fma_f32 v39, v39, s10, v214
	v_exp_f32_e32 v32, v32
	v_exp_f32_e32 v33, v33
	v_exp_f32_e32 v34, v34
	v_exp_f32_e32 v35, v35
	v_exp_f32_e32 v36, v36
	v_exp_f32_e32 v37, v37
	v_exp_f32_e32 v38, v38
	v_exp_f32_e32 v39, v39
	s_nop 0
	v_add_f32_e32 v212, v212, v32
	v_add_f32_e32 v213, v213, v33
	v_add_f32_e32 v212, v212, v34
	v_add_f32_e32 v213, v213, v35
	v_add_f32_e32 v212, v212, v36
	v_add_f32_e32 v213, v213, v37
	v_add_f32_e32 v212, v212, v38
	v_add_f32_e32 v213, v213, v39
	v_cvt_pk_bf16_f32 v32, v32, v33
	v_cvt_pk_bf16_f32 v33, v34, v35
	v_cvt_pk_bf16_f32 v34, v36, v37
	v_cvt_pk_bf16_f32 v35, v38, v39
	v_fma_f32 v40, v40, s10, v214
	v_fma_f32 v41, v41, s10, v214
	v_fma_f32 v42, v42, s10, v214
	v_fma_f32 v43, v43, s10, v214
	v_fma_f32 v44, v44, s10, v214
	v_fma_f32 v45, v45, s10, v214
	v_fma_f32 v46, v46, s10, v214
	v_fma_f32 v47, v47, s10, v214
	v_exp_f32_e32 v40, v40
	v_exp_f32_e32 v41, v41
	v_exp_f32_e32 v42, v42
	v_exp_f32_e32 v43, v43
	v_exp_f32_e32 v44, v44
	v_exp_f32_e32 v45, v45
	v_exp_f32_e32 v46, v46
	v_exp_f32_e32 v47, v47
	s_nop 0
	v_add_f32_e32 v212, v212, v40
	v_add_f32_e32 v213, v213, v41
	v_add_f32_e32 v212, v212, v42
	v_add_f32_e32 v213, v213, v43
	v_add_f32_e32 v212, v212, v44
	v_add_f32_e32 v213, v213, v45
	v_add_f32_e32 v212, v212, v46
	v_add_f32_e32 v213, v213, v47
	v_cvt_pk_bf16_f32 v40, v40, v41
	v_cvt_pk_bf16_f32 v41, v42, v43
	v_cvt_pk_bf16_f32 v42, v44, v45
	v_cvt_pk_bf16_f32 v43, v46, v47
	v_fma_f32 v48, v48, s10, v214
	v_fma_f32 v49, v49, s10, v214
	v_fma_f32 v50, v50, s10, v214
	v_fma_f32 v51, v51, s10, v214
	v_fma_f32 v52, v52, s10, v214
	v_fma_f32 v53, v53, s10, v214
	v_fma_f32 v54, v54, s10, v214
	v_fma_f32 v55, v55, s10, v214
	v_exp_f32_e32 v48, v48
	v_exp_f32_e32 v49, v49
	v_exp_f32_e32 v50, v50
	v_exp_f32_e32 v51, v51
	v_exp_f32_e32 v52, v52
	v_exp_f32_e32 v53, v53
	v_exp_f32_e32 v54, v54
	v_exp_f32_e32 v55, v55
	s_nop 0
	v_add_f32_e32 v212, v212, v48
	v_add_f32_e32 v213, v213, v49
	v_add_f32_e32 v212, v212, v50
	v_add_f32_e32 v213, v213, v51
	v_add_f32_e32 v212, v212, v52
	v_add_f32_e32 v213, v213, v53
	v_add_f32_e32 v212, v212, v54
	v_add_f32_e32 v213, v213, v55
	v_cvt_pk_bf16_f32 v48, v48, v49
	v_cvt_pk_bf16_f32 v49, v50, v51
	v_cvt_pk_bf16_f32 v50, v52, v53
	v_cvt_pk_bf16_f32 v51, v54, v55
	v_fma_f32 v56, v56, s10, v214
	v_fma_f32 v57, v57, s10, v214
	v_fma_f32 v58, v58, s10, v214
	v_fma_f32 v59, v59, s10, v214
	v_fma_f32 v60, v60, s10, v214
	v_fma_f32 v61, v61, s10, v214
	v_fma_f32 v62, v62, s10, v214
	v_fma_f32 v63, v63, s10, v214
	v_exp_f32_e32 v56, v56
	v_exp_f32_e32 v57, v57
	v_exp_f32_e32 v58, v58
	v_exp_f32_e32 v59, v59
	v_exp_f32_e32 v60, v60
	v_exp_f32_e32 v61, v61
	v_exp_f32_e32 v62, v62
	v_exp_f32_e32 v63, v63
	s_nop 0
	v_add_f32_e32 v212, v212, v56
	v_add_f32_e32 v213, v213, v57
	v_add_f32_e32 v212, v212, v58
	v_add_f32_e32 v213, v213, v59
	v_add_f32_e32 v212, v212, v60
	v_add_f32_e32 v213, v213, v61
	v_add_f32_e32 v212, v212, v62
	v_add_f32_e32 v213, v213, v63
	v_cvt_pk_bf16_f32 v56, v56, v57
	v_cvt_pk_bf16_f32 v57, v58, v59
	v_cvt_pk_bf16_f32 v58, v60, v61
	v_cvt_pk_bf16_f32 v59, v62, v63
	v_add_f32_e32 v212, v212, v213
	s_waitcnt vmcnt(15)
	v_mfma_f32_16x16x32_bf16 v[138:141], v[64:67], v[0:3], 0
	global_load_dwordx4 v[64:67], v210, s[16:17] offset:256
	s_waitcnt vmcnt(15)
	v_mfma_f32_16x16x32_bf16 v[142:145], v[68:71], v[0:3], 0
	global_load_dwordx4 v[68:71], v210, s[22:23] offset:256
	s_waitcnt vmcnt(15)
	v_mfma_f32_16x16x32_bf16 v[146:149], v[72:75], v[0:3], 0
	global_load_dwordx4 v[72:75], v210, s[26:27] offset:256
	s_waitcnt vmcnt(15)
	v_mfma_f32_16x16x32_bf16 v[150:153], v[76:79], v[0:3], 0
	global_load_dwordx4 v[76:79], v210, s[36:37] offset:256
	s_waitcnt vmcnt(15)
	v_mfma_f32_16x16x32_bf16 v[138:141], v[80:83], v[8:11], v[138:141]
	global_load_dwordx4 v[80:83], v210, s[16:17] offset:320
	s_waitcnt vmcnt(15)
	v_mfma_f32_16x16x32_bf16 v[142:145], v[84:87], v[8:11], v[142:145]
	global_load_dwordx4 v[84:87], v210, s[22:23] offset:320
	s_waitcnt vmcnt(15)
	v_mfma_f32_16x16x32_bf16 v[146:149], v[88:91], v[8:11], v[146:149]
	global_load_dwordx4 v[88:91], v210, s[26:27] offset:320
	s_waitcnt vmcnt(15)
	v_mfma_f32_16x16x32_bf16 v[150:153], v[92:95], v[8:11], v[150:153]
	global_load_dwordx4 v[92:95], v210, s[36:37] offset:320
	s_waitcnt vmcnt(15)
	v_mfma_f32_16x16x32_bf16 v[138:141], v[96:99], v[16:19], v[138:141]
	global_load_dwordx4 v[96:99], v210, s[16:17] offset:384
	s_waitcnt vmcnt(15)
	v_mfma_f32_16x16x32_bf16 v[142:145], v[100:103], v[16:19], v[142:145]
	global_load_dwordx4 v[100:103], v210, s[22:23] offset:384
	s_waitcnt vmcnt(15)
	v_mfma_f32_16x16x32_bf16 v[146:149], v[104:107], v[16:19], v[146:149]
	global_load_dwordx4 v[104:107], v210, s[26:27] offset:384
	s_waitcnt vmcnt(15)
	v_mfma_f32_16x16x32_bf16 v[150:153], v[108:111], v[16:19], v[150:153]
	global_load_dwordx4 v[108:111], v210, s[36:37] offset:384
	s_waitcnt vmcnt(15)
	v_mfma_f32_16x16x32_bf16 v[138:141], v[112:115], v[24:27], v[138:141]
	global_load_dwordx4 v[112:115], v210, s[16:17] offset:448
	s_waitcnt vmcnt(15)
	v_mfma_f32_16x16x32_bf16 v[142:145], v[116:119], v[24:27], v[142:145]
	global_load_dwordx4 v[116:119], v210, s[22:23] offset:448
	s_waitcnt vmcnt(15)
	v_mfma_f32_16x16x32_bf16 v[146:149], v[120:123], v[24:27], v[146:149]
	global_load_dwordx4 v[120:123], v210, s[26:27] offset:448
	s_waitcnt vmcnt(15)
	v_mfma_f32_16x16x32_bf16 v[150:153], v[124:127], v[24:27], v[150:153]
	global_load_dwordx4 v[124:127], v210, s[36:37] offset:448
	s_waitcnt vmcnt(15)
	v_mfma_f32_16x16x32_bf16 v[138:141], v[64:67], v[32:35], v[138:141]
	s_waitcnt vmcnt(14)
	v_mfma_f32_16x16x32_bf16 v[142:145], v[68:71], v[32:35], v[142:145]
	s_waitcnt vmcnt(13)
	v_mfma_f32_16x16x32_bf16 v[146:149], v[72:75], v[32:35], v[146:149]
	s_waitcnt vmcnt(12)
	v_mfma_f32_16x16x32_bf16 v[150:153], v[76:79], v[32:35], v[150:153]
	s_waitcnt vmcnt(11)
	v_mfma_f32_16x16x32_bf16 v[138:141], v[80:83], v[40:43], v[138:141]
	s_waitcnt vmcnt(10)
	v_mfma_f32_16x16x32_bf16 v[142:145], v[84:87], v[40:43], v[142:145]
	s_waitcnt vmcnt(9)
	v_mfma_f32_16x16x32_bf16 v[146:149], v[88:91], v[40:43], v[146:149]
	s_waitcnt vmcnt(8)
	v_mfma_f32_16x16x32_bf16 v[150:153], v[92:95], v[40:43], v[150:153]
	s_waitcnt vmcnt(7)
	v_mfma_f32_16x16x32_bf16 v[138:141], v[96:99], v[48:51], v[138:141]
	s_waitcnt vmcnt(6)
	v_mfma_f32_16x16x32_bf16 v[142:145], v[100:103], v[48:51], v[142:145]
	s_waitcnt vmcnt(5)
	v_mfma_f32_16x16x32_bf16 v[146:149], v[104:107], v[48:51], v[146:149]
	s_waitcnt vmcnt(4)
	v_mfma_f32_16x16x32_bf16 v[150:153], v[108:111], v[48:51], v[150:153]
	s_waitcnt vmcnt(3)
	v_mfma_f32_16x16x32_bf16 v[138:141], v[112:115], v[56:59], v[138:141]
	s_waitcnt vmcnt(2)
	v_mfma_f32_16x16x32_bf16 v[142:145], v[116:119], v[56:59], v[142:145]
	s_waitcnt vmcnt(1)
	v_mfma_f32_16x16x32_bf16 v[146:149], v[120:123], v[56:59], v[146:149]
	s_waitcnt vmcnt(0)
	v_mfma_f32_16x16x32_bf16 v[150:153], v[124:127], v[56:59], v[150:153]
	ds_bpermute_b32 v136, v215, v212
	s_waitcnt lgkmcnt(0)
	v_add_f32_e32 v212, v212, v136
	ds_bpermute_b32 v136, v216, v212
	s_waitcnt lgkmcnt(0)
	v_add_f32_e32 v212, v212, v136
	v_rcp_f32_e32 v213, v212
	s_nop 0
	v_fma_f32 v136, -v212, v213, 1.0
	v_fma_f32 v213, v136, v213, v213
	v_mul_u32_u24_e32 v208, 0x600, v206
	v_lshl_add_u32 v208, v207, 3, v208
	s_add_u32 s10, s4, s38
	s_addc_u32 s11, s5, 0
	s_nop 2
	v_mul_f32_e32 v138, v138, v213
	v_mul_f32_e32 v139, v139, v213
	v_mul_f32_e32 v140, v140, v213
	v_mul_f32_e32 v141, v141, v213
	v_cvt_pk_bf16_f32 v138, v138, v139
	v_cvt_pk_bf16_f32 v139, v140, v141
	global_store_dwordx2 v208, v[138:139], s[10:11] offset:0
	v_mul_f32_e32 v142, v142, v213
	v_mul_f32_e32 v143, v143, v213
	v_mul_f32_e32 v144, v144, v213
	v_mul_f32_e32 v145, v145, v213
	v_cvt_pk_bf16_f32 v142, v142, v143
	v_cvt_pk_bf16_f32 v143, v144, v145
	global_store_dwordx2 v208, v[142:143], s[10:11] offset:32
	v_mul_f32_e32 v146, v146, v213
	v_mul_f32_e32 v147, v147, v213
	v_mul_f32_e32 v148, v148, v213
	v_mul_f32_e32 v149, v149, v213
	v_cvt_pk_bf16_f32 v146, v146, v147
	v_cvt_pk_bf16_f32 v147, v148, v149
	global_store_dwordx2 v208, v[146:147], s[10:11] offset:64
	v_mul_f32_e32 v150, v150, v213
	v_mul_f32_e32 v151, v151, v213
	v_mul_f32_e32 v152, v152, v213
	v_mul_f32_e32 v153, v153, v213
	v_cvt_pk_bf16_f32 v150, v150, v151
	v_cvt_pk_bf16_f32 v151, v152, v153
	global_store_dwordx2 v208, v[150:151], s[10:11] offset:96
	s_branch .LBB0_443
